# prepass weight-conversion loop rotated: next four tiles decoded and their loads issued before the current group is read back from LDS and stored
# speedup vs baseline: 1.0098x; 1.0098x over previous
; #define LAS __attribute__((address_space(3)))
; __device__ __forceinline__ int fresh_bid() { int t = blockIdx.x; asm volatile("" : "+s"(t)); return t; }
; __device__ __forceinline__ unsigned cvt_pk_bf16(float lo, float hi) { const f32x2 v = {lo, hi}; const bf16x2_t b = __builtin_convertvector(v, bf16x2_t); return __builtin_bit_cast(unsigned, b); }
; __device__ __forceinline__ void conv_weights(ParamsK p, LAS float* T) {
;     ...
;     for (int id0 = fresh_bid() * 4; id0 < TOTAL; id0 += gridDim.x * 4) {
;         f32x4 v[4][2]; bf16_t* dstp[4];
; #pragma unroll
;         for (int u = 0; u < 4; ++u) {
;             const ConvTile c = conv_decode(p, id0 + u);
;             dstp[u] = c.dst + (size_t)n * c.ldt + k8;
; #pragma unroll
;             for (int ps = 0; ps < 2; ++ps) { v[u][ps] = (f32x4){0.f, 0.f, 0.f, 0.f}; if (n4 < c.valid) v[u][ps] = __builtin_nontemporal_load((const f32x4*)(c.src + (size_t)(kk + 32 * ps) * c.ldw + n4)); }
;         }
; #pragma unroll
;         for (int u = 0; u < 4; ++u)
; #pragma unroll
;             for (int ps = 0; ps < 2; ++ps) { LAS float* tp = T + u * 4160 + (kk + 32 * ps) * 65 + n4; tp[0] = v[u][ps][0]; tp[1] = v[u][ps][1]; tp[2] = v[u][ps][2]; tp[3] = v[u][ps][3]; }
;         __syncthreads();
; #pragma unroll
;         for (int u = 0; u < 4; ++u) {
;             const LAS float* tp = T + u * 4160 + k8 * 65 + n;
;             u32x4 w;
;             w.x = cvt_pk_bf16(tp[0 * 65], tp[1 * 65]); w.y = cvt_pk_bf16(tp[2 * 65], tp[3 * 65]); w.z = cvt_pk_bf16(tp[4 * 65], tp[5 * 65]); w.w = cvt_pk_bf16(tp[6 * 65], tp[7 * 65]);
;             *(u32x4*)dstp[u] = w;
;         }
;         __syncthreads();
.LBB0_5:
	s_or_b64 exec, exec, s[4:5]
	s_mov_b64 s[12:13], s[84:85]
	v_mov_b32_e32 v1, v176
	s_mov_b32 s6, s94
	s_cmpk_gt_i32 s6, 0x243f
	s_cbranch_scc1 .LBB0_109
	v_ashrrev_i32_e32 v34, 4, v1
	v_ashrrev_i32_e32 v36, 3, v1
	v_lshlrev_b32_e32 v2, 3, v1
	v_lshlrev_b32_e32 v1, 2, v1
	s_movk_i32 s7, 0x104
	v_and_b32_e32 v2, 56, v2
	v_and_b32_e32 v4, 60, v1
	v_mul_lo_u32 v46, v34, s7
	v_lshl_add_u32 v3, v36, 2, 0
	v_lshl_add_u32 v41, v4, 2, 0
	v_mul_u32_u24_e32 v5, 0x104, v2
	v_add_u32_e32 v40, 32, v34
	v_add_u32_e32 v6, 0x2080, v46
	s_lshl_b32 s7, s6, 3
	s_lshl_b32 s3, s74, 2
	s_lshl_b32 s33, s6, 2
	s_mov_b32 s9, 0
	v_ashrrev_i32_e32 v1, 31, v36
	v_mov_b32_e32 v39, 0
	v_cmp_gt_u32_e64 s[4:5], 16, v4
	v_ashrrev_i32_e32 v35, 31, v34
	v_ashrrev_i32_e32 v37, 31, v40
	s_lshl_b32 s38, s6, 8
	s_lshl_b32 s39, s74, 8
	s_or_b32 s52, s7, 6
	s_lshl_b32 s53, s74, 3
	s_lshl_b32 s54, s6, 4
	s_lshl_b32 s55, s74, 4
	s_movk_i32 s56, 0xd0
	s_movk_i32 s57, 0xb8
	s_mov_b32 s58, 0x7e00000
	v_lshlrev_b32_e32 v38, 2, v4
	v_lshlrev_b32_e32 v42, 1, v2
	v_add_u32_e32 v47, v41, v6
	v_add_u32_e32 v48, v3, v5
	s_mov_b32 s66, 0
	s_branch .LBB0_8
.LBB0_7:
	s_lshl_b64 s[6:7], s[44:45], 1
	s_add_u32 s6, s40, s6
	v_mul_lo_u32 v43, s47, v36
	v_mul_lo_u32 v49, s46, v1
	v_mad_u64_u32 v[44:45], s[14:15], s46, v36, 0
	s_addc_u32 s7, s41, s7
	v_add3_u32 v45, v45, v49, v43
	v_lshl_add_u64 v[44:45], v[44:45], 1, s[6:7]
	s_lshl_b64 s[6:7], s[28:29], 1
	s_add_u32 s6, s26, s6
	v_mul_lo_u32 v43, s31, v36
	v_mul_lo_u32 v49, s30, v1
	v_mad_u64_u32 v[50:51], s[14:15], s30, v36, 0
	s_addc_u32 s7, s27, s7
	v_add3_u32 v51, v51, v49, v43
	v_lshl_add_u64 v[50:51], v[50:51], 1, s[6:7]
	s_lshl_b64 s[6:7], s[22:23], 1
	s_add_u32 s6, s20, s6
	v_mul_lo_u32 v49, s25, v36
	v_mul_lo_u32 v54, s24, v1
	v_mad_u64_u32 v[52:53], s[14:15], s24, v36, 0
	s_addc_u32 s7, s21, s7
	v_add3_u32 v53, v53, v54, v49
	v_lshl_add_u64 v[52:53], v[52:53], 1, s[6:7]
	s_lshl_b64 s[6:7], s[16:17], 1
	s_add_u32 s6, s10, s6
	s_addc_u32 s7, s11, s7
	v_mul_lo_u32 v49, s19, v36
	v_mul_lo_u32 v56, s18, v1
	v_mad_u64_u32 v[54:55], s[10:11], s18, v36, 0
	v_add3_u32 v55, v55, v56, v49
	v_mov_b32_e32 v43, v39
	v_lshl_add_u64 v[54:55], v[54:55], 1, s[6:7]
	v_lshl_add_u64 v[200:201], v[54:55], 0, v[42:43]
	v_lshl_add_u64 v[202:203], v[52:53], 0, v[42:43]
	v_lshl_add_u64 v[204:205], v[50:51], 0, v[42:43]
	v_lshl_add_u64 v[206:207], v[44:45], 0, v[42:43]
	v_add_u32_e32 v49, v41, v46
	s_waitcnt vmcnt(4)
	ds_write2_b32 v49, v6, v7 offset1:1
	ds_write2_b32 v49, v8, v9 offset0:2 offset1:3
	ds_write2_b32 v47, v2, v3 offset1:1
	ds_write2_b32 v47, v4, v5 offset0:2 offset1:3
	v_add_u32_e32 v2, 0x4100, v49
	ds_write2_b32 v2, v14, v15 offset1:1
	v_add_u32_e32 v2, 0x4108, v49
	ds_write2_b32 v2, v16, v17 offset1:1
	v_add_u32_e32 v2, 0x4100, v47
	ds_write2_b32 v2, v10, v11 offset1:1
	v_add_u32_e32 v2, 0x4108, v47
	ds_write2_b32 v2, v12, v13 offset1:1
	v_add_u32_e32 v2, 0x8200, v49
	ds_write2_b32 v2, v22, v23 offset1:1
	v_add_u32_e32 v2, 0x8208, v49
	ds_write2_b32 v2, v24, v25 offset1:1
	v_add_u32_e32 v2, 0x8200, v47
	ds_write2_b32 v2, v18, v19 offset1:1
	v_add_u32_e32 v2, 0x8208, v47
	ds_write2_b32 v2, v20, v21 offset1:1
	v_add_u32_e32 v2, 0xc300, v49
	ds_write2_b32 v2, v30, v31 offset1:1
	v_add_u32_e32 v2, 0xc308, v49
	ds_write2_b32 v2, v32, v33 offset1:1
	v_add_u32_e32 v2, 0xc300, v47
	ds_write2_b32 v2, v26, v27 offset1:1
	v_add_u32_e32 v2, 0xc308, v47
	ds_write2_b32 v2, v28, v29 offset1:1
	s_waitcnt lgkmcnt(0)
	s_barrier
	s_add_i32 s33, s33, s3
	s_add_i32 s38, s38, s39
	s_add_i32 s52, s52, s53
	s_add_i32 s54, s54, s55
	s_cmp_lt_i32 s33, 0x9100
	s_cselect_b32 s65, 1, 0
	s_mov_b32 s66, 1
	s_cbranch_scc1 .LBB0_8
.Lconv_read:
	ds_read2_b32 v[208:209], v48 offset1:65
	ds_read2_b32 v[210:211], v48 offset0:130 offset1:195
	v_add_u32_e32 v214, 0x400, v48
	ds_read2_b32 v[212:213], v214 offset0:4 offset1:69
	ds_read2_b32 v[214:215], v214 offset0:134 offset1:199
	v_add_u32_e32 v216, 0x4400, v48
	s_waitcnt lgkmcnt(3)
	v_cvt_pk_bf16_f32 v208, v208, v209
	s_waitcnt lgkmcnt(2)
	v_cvt_pk_bf16_f32 v209, v210, v211
	s_waitcnt lgkmcnt(1)
	v_cvt_pk_bf16_f32 v210, v212, v213
	v_add_u32_e32 v212, 0x4000, v48
	v_add_u32_e32 v218, 0x4600, v48
	s_waitcnt lgkmcnt(0)
	v_cvt_pk_bf16_f32 v211, v214, v215
	ds_read2_b32 v[212:213], v212 offset0:64 offset1:129
	v_add_u32_e32 v214, 0x4200, v48
	ds_read2_b32 v[216:217], v216 offset0:68 offset1:133
	ds_read2_b32 v[218:219], v218 offset0:70 offset1:135
	ds_read2_b32 v[214:215], v214 offset0:66 offset1:131
	global_store_dwordx4 v[200:201], v[208:211], off
	s_nop 1
	s_waitcnt lgkmcnt(3)
	v_cvt_pk_bf16_f32 v208, v212, v213
	s_waitcnt lgkmcnt(2)
	v_cvt_pk_bf16_f32 v210, v216, v217
	s_waitcnt lgkmcnt(1)
	v_cvt_pk_bf16_f32 v211, v218, v219
	v_add_u32_e32 v212, 0x8000, v48
	v_add_u32_e32 v216, 0x8400, v48
	v_add_u32_e32 v218, 0x8800, v48
	s_waitcnt lgkmcnt(0)
	v_cvt_pk_bf16_f32 v209, v214, v215
	ds_read2_b32 v[212:213], v212 offset0:128 offset1:193
	ds_read2_b32 v[214:215], v216 offset0:2 offset1:67
	ds_read2_b32 v[216:217], v216 offset0:132 offset1:197
	ds_read2_b32 v[218:219], v218 offset0:6 offset1:71
	global_store_dwordx4 v[202:203], v[208:211], off
	s_nop 0
	s_nop 0
	s_waitcnt lgkmcnt(3)
	v_cvt_pk_bf16_f32 v208, v212, v213
	s_waitcnt lgkmcnt(2)
	v_cvt_pk_bf16_f32 v209, v214, v215
	s_waitcnt lgkmcnt(1)
	v_cvt_pk_bf16_f32 v210, v216, v217
	s_waitcnt lgkmcnt(0)
	v_cvt_pk_bf16_f32 v211, v218, v219
	v_add_u32_e32 v212, 0xc200, v48
	v_add_u32_e32 v214, 0xc400, v48
	v_add_u32_e32 v216, 0xc600, v48
	v_add_u32_e32 v218, 0xc800, v48
	ds_read2_b32 v[212:213], v212 offset0:64 offset1:129
	ds_read2_b32 v[214:215], v214 offset0:66 offset1:131
	ds_read2_b32 v[216:217], v216 offset0:68 offset1:133
	ds_read2_b32 v[218:219], v218 offset0:70 offset1:135
	s_nop 0
	s_nop 0
	global_store_dwordx4 v[204:205], v[208:211], off
	s_nop 0
	s_waitcnt lgkmcnt(3)
	v_cvt_pk_bf16_f32 v208, v212, v213
	s_waitcnt lgkmcnt(2)
	v_cvt_pk_bf16_f32 v209, v214, v215
	s_waitcnt lgkmcnt(1)
	v_cvt_pk_bf16_f32 v210, v216, v217
	s_waitcnt lgkmcnt(0)
	v_cvt_pk_bf16_f32 v211, v218, v219
	global_store_dwordx4 v[206:207], v[208:211], off
	s_barrier
	s_cmp_lg_u32 s65, 0
	s_cbranch_scc1 .LBB0_7
	s_branch .LBB0_109
.Lconv_dec_done:
	s_cmp_lg_u32 s66, 0
	s_cbranch_scc1 .Lconv_read
	s_waitcnt vmcnt(0)
	s_branch .LBB0_7
